# stream unit: one 4-load group in flight per wave (loads re-issued behind each converted group, scalar base + lane offset, SGPR page table, 8KB per-workgroup in-page phase); attention selfmax removal
# speedup vs baseline: 1.0087x; 1.0054x over previous
.LBB0_539:
	s_add_i32 s25, s24, 1
	s_cmp_eq_u32 s24, 15
	s_cbranch_scc1 .Lsp_last_a
	s_waitcnt vmcnt(0)
	v_cvt_pk_bf16_f32 v244, v18, v19
	v_cvt_pk_bf16_f32 v245, v20, v21
	ds_write_b64 v194, v[244:245]
	v_cvt_pk_bf16_f32 v180, v22, v23
	v_cvt_pk_bf16_f32 v181, v24, v25
	ds_write_b64 v195, v[180:181] offset:8192
	v_cvt_pk_bf16_f32 v244, v26, v27
	v_cvt_pk_bf16_f32 v245, v28, v29
	ds_write_b64 v196, v[244:245]
	v_cvt_pk_bf16_f32 v180, v34, v35
	v_cvt_pk_bf16_f32 v181, v36, v37
	ds_write_b64 v197, v[180:181] offset:8192
	s_add_u32 s30, s95, s94
	s_add_u32 s26, s72, s30
	s_addc_u32 s27, s73, 0
	s_add_u32 s28, s74, s30
	s_addc_u32 s29, s75, 0
	s_add_u32 s94, s94, 0x2000
	s_and_b32 s94, s94, 0x3ffff
	global_load_dwordx4 v[30:33], v184, s[26:27] offset:-4096 nt
	global_load_dwordx4 v[38:41], v184, s[28:29] offset:-4096 nt
	global_load_dwordx4 v[42:45], v184, s[26:27] nt
	global_load_dwordx4 v[50:53], v184, s[28:29] nt
	s_waitcnt vmcnt(0)
	v_cvt_pk_bf16_f32 v244, v30, v31
	v_cvt_pk_bf16_f32 v245, v32, v33
	ds_write_b64 v198, v[244:245]
	v_cvt_pk_bf16_f32 v180, v38, v39
	v_cvt_pk_bf16_f32 v181, v40, v41
	ds_write_b64 v199, v[180:181] offset:8192
	v_cvt_pk_bf16_f32 v244, v42, v43
	v_cvt_pk_bf16_f32 v245, v44, v45
	ds_write_b64 v200, v[244:245]
	v_cvt_pk_bf16_f32 v180, v50, v51
	v_cvt_pk_bf16_f32 v181, v52, v53
	ds_write_b64 v201, v[180:181] offset:8192
	s_add_u32 s30, s95, s94
	s_add_u32 s26, s72, s30
	s_addc_u32 s27, s73, 0
	s_add_u32 s28, s74, s30
	s_addc_u32 s29, s75, 0
	s_add_u32 s94, s94, 0x2000
	s_and_b32 s94, s94, 0x3ffff
	global_load_dwordx4 v[46:49], v184, s[26:27] offset:-4096 nt
	global_load_dwordx4 v[54:57], v184, s[28:29] offset:-4096 nt
	global_load_dwordx4 v[58:61], v184, s[26:27] nt
	global_load_dwordx4 v[66:69], v184, s[28:29] nt
	s_waitcnt vmcnt(0)
	v_cvt_pk_bf16_f32 v244, v46, v47
	v_cvt_pk_bf16_f32 v245, v48, v49
	ds_write_b64 v202, v[244:245]
	v_cvt_pk_bf16_f32 v180, v54, v55
	v_cvt_pk_bf16_f32 v181, v56, v57
	ds_write_b64 v203, v[180:181] offset:8192
	v_cvt_pk_bf16_f32 v244, v58, v59
	v_cvt_pk_bf16_f32 v245, v60, v61
	ds_write_b64 v204, v[244:245]
	v_cvt_pk_bf16_f32 v180, v66, v67
	v_cvt_pk_bf16_f32 v181, v68, v69
	ds_write_b64 v205, v[180:181] offset:8192
	s_add_u32 s30, s95, s94
	s_add_u32 s26, s72, s30
	s_addc_u32 s27, s73, 0
	s_add_u32 s28, s74, s30
	s_addc_u32 s29, s75, 0
	s_add_u32 s94, s94, 0x2000
	s_and_b32 s94, s94, 0x3ffff
	global_load_dwordx4 v[62:65], v184, s[26:27] offset:-4096 nt
	global_load_dwordx4 v[70:73], v184, s[28:29] offset:-4096 nt
	global_load_dwordx4 v[74:77], v184, s[26:27] nt
	global_load_dwordx4 v[82:85], v184, s[28:29] nt
	s_waitcnt vmcnt(0)
	v_cvt_pk_bf16_f32 v244, v62, v63
	v_cvt_pk_bf16_f32 v245, v64, v65
	ds_write_b64 v206, v[244:245]
	v_cvt_pk_bf16_f32 v180, v70, v71
	v_cvt_pk_bf16_f32 v181, v72, v73
	ds_write_b64 v207, v[180:181] offset:8192
	v_cvt_pk_bf16_f32 v244, v74, v75
	v_cvt_pk_bf16_f32 v245, v76, v77
	ds_write_b64 v208, v[244:245]
	v_cvt_pk_bf16_f32 v180, v82, v83
	v_cvt_pk_bf16_f32 v181, v84, v85
	ds_write_b64 v209, v[180:181] offset:8192
	s_add_u32 s30, s95, s94
	s_add_u32 s26, s72, s30
	s_addc_u32 s27, s73, 0
	s_add_u32 s28, s74, s30
	s_addc_u32 s29, s75, 0
	s_add_u32 s94, s94, 0x2000
	s_and_b32 s94, s94, 0x3ffff
	global_load_dwordx4 v[78:81], v184, s[26:27] offset:-4096 nt
	global_load_dwordx4 v[86:89], v184, s[28:29] offset:-4096 nt
	global_load_dwordx4 v[90:93], v184, s[26:27] nt
	global_load_dwordx4 v[110:113], v184, s[28:29] nt
	s_waitcnt vmcnt(0)
	v_cvt_pk_bf16_f32 v244, v78, v79
	v_cvt_pk_bf16_f32 v245, v80, v81
	ds_write_b64 v194, v[244:245] offset:4096
	v_cvt_pk_bf16_f32 v180, v86, v87
	v_cvt_pk_bf16_f32 v181, v88, v89
	ds_write_b64 v195, v[180:181] offset:12288
	v_cvt_pk_bf16_f32 v244, v90, v91
	v_cvt_pk_bf16_f32 v245, v92, v93
	ds_write_b64 v210, v[244:245]
	v_cvt_pk_bf16_f32 v180, v110, v111
	v_cvt_pk_bf16_f32 v181, v112, v113
	ds_write_b64 v211, v[180:181] offset:8192
	s_add_u32 s30, s95, s94
	s_add_u32 s26, s72, s30
	s_addc_u32 s27, s73, 0
	s_add_u32 s28, s74, s30
	s_addc_u32 s29, s75, 0
	s_add_u32 s94, s94, 0x2000
	s_and_b32 s94, s94, 0x3ffff
	global_load_dwordx4 v[106:109], v184, s[26:27] offset:-4096 nt
	global_load_dwordx4 v[118:121], v184, s[28:29] offset:-4096 nt
	global_load_dwordx4 v[138:141], v184, s[26:27] nt
	global_load_dwordx4 v[142:145], v184, s[28:29] nt
	s_waitcnt vmcnt(0)
	v_cvt_pk_bf16_f32 v244, v106, v107
	v_cvt_pk_bf16_f32 v245, v108, v109
	ds_write_b64 v212, v[244:245]
	v_cvt_pk_bf16_f32 v180, v118, v119
	v_cvt_pk_bf16_f32 v181, v120, v121
	ds_write_b64 v213, v[180:181] offset:8192
	v_cvt_pk_bf16_f32 v244, v138, v139
	v_cvt_pk_bf16_f32 v245, v140, v141
	ds_write_b64 v214, v[244:245]
	v_cvt_pk_bf16_f32 v180, v142, v143
	v_cvt_pk_bf16_f32 v181, v144, v145
	ds_write_b64 v215, v[180:181] offset:8192
	s_add_u32 s30, s95, s94
	s_add_u32 s26, s72, s30
	s_addc_u32 s27, s73, 0
	s_add_u32 s28, s74, s30
	s_addc_u32 s29, s75, 0
	s_add_u32 s94, s94, 0x2000
	s_and_b32 s94, s94, 0x3ffff
	global_load_dwordx4 v[146:149], v184, s[26:27] offset:-4096 nt
	global_load_dwordx4 v[150:153], v184, s[28:29] offset:-4096 nt
	global_load_dwordx4 v[154:157], v184, s[26:27] nt
	global_load_dwordx4 v[158:161], v184, s[28:29] nt
	s_waitcnt vmcnt(0)
	v_cvt_pk_bf16_f32 v244, v146, v147
	v_cvt_pk_bf16_f32 v245, v148, v149
	ds_write_b64 v216, v[244:245]
	v_cvt_pk_bf16_f32 v180, v150, v151
	v_cvt_pk_bf16_f32 v181, v152, v153
	ds_write_b64 v217, v[180:181] offset:8192
	v_cvt_pk_bf16_f32 v244, v154, v155
	v_cvt_pk_bf16_f32 v245, v156, v157
	ds_write_b64 v218, v[244:245]
	v_cvt_pk_bf16_f32 v180, v158, v159
	v_cvt_pk_bf16_f32 v181, v160, v161
	ds_write_b64 v219, v[180:181] offset:8192
	s_add_u32 s30, s95, s94
	s_add_u32 s26, s72, s30
	s_addc_u32 s27, s73, 0
	s_add_u32 s28, s74, s30
	s_addc_u32 s29, s75, 0
	s_add_u32 s94, s94, 0x2000
	s_and_b32 s94, s94, 0x3ffff
	global_load_dwordx4 v[162:165], v184, s[26:27] offset:-4096 nt
	global_load_dwordx4 v[166:169], v184, s[28:29] offset:-4096 nt
	global_load_dwordx4 v[170:173], v184, s[26:27] nt
	global_load_dwordx4 v[174:177], v184, s[28:29] nt
	s_lshr_b32 s30, s25, 2
	s_cmp_lt_u32 s30, 2
	s_cselect_b32 s95, s98, s100
	s_cselect_b32 s97, s99, s101
	s_bitcmp1_b32 s30, 0
	s_cselect_b32 s95, s97, s95
	s_lshl_b32 s95, s95, 18
	s_add_u32 s95, s95, 0x1000
	s_waitcnt vmcnt(0)
	v_cvt_pk_bf16_f32 v244, v162, v163
	v_cvt_pk_bf16_f32 v245, v164, v165
	ds_write_b64 v220, v[244:245]
	v_cvt_pk_bf16_f32 v180, v166, v167
	v_cvt_pk_bf16_f32 v181, v168, v169
	ds_write_b64 v221, v[180:181] offset:8192
	v_cvt_pk_bf16_f32 v244, v170, v171
	v_cvt_pk_bf16_f32 v245, v172, v173
	ds_write_b64 v227, v[244:245]
	v_cvt_pk_bf16_f32 v180, v174, v175
	v_cvt_pk_bf16_f32 v181, v176, v177
	ds_write_b64 v228, v[180:181] offset:8192
	s_add_u32 s30, s95, s94
	s_add_u32 s26, s72, s30
	s_addc_u32 s27, s73, 0
	s_add_u32 s28, s74, s30
	s_addc_u32 s29, s75, 0
	s_add_u32 s94, s94, 0x2000
	s_and_b32 s94, s94, 0x3ffff
	global_load_dwordx4 v[18:21], v184, s[26:27] offset:-4096 nt
	global_load_dwordx4 v[22:25], v184, s[28:29] offset:-4096 nt
	global_load_dwordx4 v[26:29], v184, s[26:27] nt
	global_load_dwordx4 v[34:37], v184, s[28:29] nt
	s_branch .LBB0_543
.Lsp_last_a:
	s_waitcnt vmcnt(0)
	v_cvt_pk_bf16_f32 v244, v18, v19
	v_cvt_pk_bf16_f32 v245, v20, v21
	ds_write_b64 v194, v[244:245]
	v_cvt_pk_bf16_f32 v180, v22, v23
	v_cvt_pk_bf16_f32 v181, v24, v25
	ds_write_b64 v195, v[180:181] offset:8192
	v_cvt_pk_bf16_f32 v244, v26, v27
	v_cvt_pk_bf16_f32 v245, v28, v29
	ds_write_b64 v196, v[244:245]
	v_cvt_pk_bf16_f32 v180, v34, v35
	v_cvt_pk_bf16_f32 v181, v36, v37
	ds_write_b64 v197, v[180:181] offset:8192
	s_add_u32 s30, s95, s94
	s_add_u32 s26, s72, s30
	s_addc_u32 s27, s73, 0
	s_add_u32 s28, s74, s30
	s_addc_u32 s29, s75, 0
	s_add_u32 s94, s94, 0x2000
	s_and_b32 s94, s94, 0x3ffff
	global_load_dwordx4 v[30:33], v184, s[26:27] offset:-4096 nt
	global_load_dwordx4 v[38:41], v184, s[28:29] offset:-4096 nt
	global_load_dwordx4 v[42:45], v184, s[26:27] nt
	global_load_dwordx4 v[50:53], v184, s[28:29] nt
	s_waitcnt vmcnt(0)
	v_cvt_pk_bf16_f32 v244, v30, v31
	v_cvt_pk_bf16_f32 v245, v32, v33
	ds_write_b64 v198, v[244:245]
	v_cvt_pk_bf16_f32 v180, v38, v39
	v_cvt_pk_bf16_f32 v181, v40, v41
	ds_write_b64 v199, v[180:181] offset:8192
	v_cvt_pk_bf16_f32 v244, v42, v43
	v_cvt_pk_bf16_f32 v245, v44, v45
	ds_write_b64 v200, v[244:245]
	v_cvt_pk_bf16_f32 v180, v50, v51
	v_cvt_pk_bf16_f32 v181, v52, v53
	ds_write_b64 v201, v[180:181] offset:8192
	s_add_u32 s30, s95, s94
	s_add_u32 s26, s72, s30
	s_addc_u32 s27, s73, 0
	s_add_u32 s28, s74, s30
	s_addc_u32 s29, s75, 0
	s_add_u32 s94, s94, 0x2000
	s_and_b32 s94, s94, 0x3ffff
	global_load_dwordx4 v[46:49], v184, s[26:27] offset:-4096 nt
	global_load_dwordx4 v[54:57], v184, s[28:29] offset:-4096 nt
	global_load_dwordx4 v[58:61], v184, s[26:27] nt
	global_load_dwordx4 v[66:69], v184, s[28:29] nt
	s_waitcnt vmcnt(0)
	v_cvt_pk_bf16_f32 v244, v46, v47
	v_cvt_pk_bf16_f32 v245, v48, v49
	ds_write_b64 v202, v[244:245]
	v_cvt_pk_bf16_f32 v180, v54, v55
	v_cvt_pk_bf16_f32 v181, v56, v57
	ds_write_b64 v203, v[180:181] offset:8192
	v_cvt_pk_bf16_f32 v244, v58, v59
	v_cvt_pk_bf16_f32 v245, v60, v61
	ds_write_b64 v204, v[244:245]
	v_cvt_pk_bf16_f32 v180, v66, v67
	v_cvt_pk_bf16_f32 v181, v68, v69
	ds_write_b64 v205, v[180:181] offset:8192
	s_add_u32 s30, s95, s94
	s_add_u32 s26, s72, s30
	s_addc_u32 s27, s73, 0
	s_add_u32 s28, s74, s30
	s_addc_u32 s29, s75, 0
	s_add_u32 s94, s94, 0x2000
	s_and_b32 s94, s94, 0x3ffff
	global_load_dwordx4 v[62:65], v184, s[26:27] offset:-4096 nt
	global_load_dwordx4 v[70:73], v184, s[28:29] offset:-4096 nt
	global_load_dwordx4 v[74:77], v184, s[26:27] nt
	global_load_dwordx4 v[82:85], v184, s[28:29] nt
	s_waitcnt vmcnt(0)
	v_cvt_pk_bf16_f32 v244, v62, v63
	v_cvt_pk_bf16_f32 v245, v64, v65
	ds_write_b64 v206, v[244:245]
	v_cvt_pk_bf16_f32 v180, v70, v71
	v_cvt_pk_bf16_f32 v181, v72, v73
	ds_write_b64 v207, v[180:181] offset:8192
	v_cvt_pk_bf16_f32 v244, v74, v75
	v_cvt_pk_bf16_f32 v245, v76, v77
	ds_write_b64 v208, v[244:245]
	v_cvt_pk_bf16_f32 v180, v82, v83
	v_cvt_pk_bf16_f32 v181, v84, v85
	ds_write_b64 v209, v[180:181] offset:8192
	s_add_u32 s30, s95, s94
	s_add_u32 s26, s72, s30
	s_addc_u32 s27, s73, 0
	s_add_u32 s28, s74, s30
	s_addc_u32 s29, s75, 0
	s_add_u32 s94, s94, 0x2000
	s_and_b32 s94, s94, 0x3ffff
	global_load_dwordx4 v[78:81], v184, s[26:27] offset:-4096 nt
	global_load_dwordx4 v[86:89], v184, s[28:29] offset:-4096 nt
	global_load_dwordx4 v[90:93], v184, s[26:27] nt
	global_load_dwordx4 v[110:113], v184, s[28:29] nt
	s_waitcnt vmcnt(0)
	v_cvt_pk_bf16_f32 v244, v78, v79
	v_cvt_pk_bf16_f32 v245, v80, v81
	ds_write_b64 v194, v[244:245] offset:4096
	v_cvt_pk_bf16_f32 v180, v86, v87
	v_cvt_pk_bf16_f32 v181, v88, v89
	ds_write_b64 v195, v[180:181] offset:12288
	v_cvt_pk_bf16_f32 v244, v90, v91
	v_cvt_pk_bf16_f32 v245, v92, v93
	ds_write_b64 v210, v[244:245]
	v_cvt_pk_bf16_f32 v180, v110, v111
	v_cvt_pk_bf16_f32 v181, v112, v113
	ds_write_b64 v211, v[180:181] offset:8192
	s_add_u32 s30, s95, s94
	s_add_u32 s26, s72, s30
	s_addc_u32 s27, s73, 0
	s_add_u32 s28, s74, s30
	s_addc_u32 s29, s75, 0
	s_add_u32 s94, s94, 0x2000
	s_and_b32 s94, s94, 0x3ffff
	global_load_dwordx4 v[106:109], v184, s[26:27] offset:-4096 nt
	global_load_dwordx4 v[118:121], v184, s[28:29] offset:-4096 nt
	global_load_dwordx4 v[138:141], v184, s[26:27] nt
	global_load_dwordx4 v[142:145], v184, s[28:29] nt
	s_waitcnt vmcnt(0)
	v_cvt_pk_bf16_f32 v244, v106, v107
	v_cvt_pk_bf16_f32 v245, v108, v109
	ds_write_b64 v212, v[244:245]
	v_cvt_pk_bf16_f32 v180, v118, v119
	v_cvt_pk_bf16_f32 v181, v120, v121
	ds_write_b64 v213, v[180:181] offset:8192
	v_cvt_pk_bf16_f32 v244, v138, v139
	v_cvt_pk_bf16_f32 v245, v140, v141
	ds_write_b64 v214, v[244:245]
	v_cvt_pk_bf16_f32 v180, v142, v143
	v_cvt_pk_bf16_f32 v181, v144, v145
	ds_write_b64 v215, v[180:181] offset:8192
	s_add_u32 s30, s95, s94
	s_add_u32 s26, s72, s30
	s_addc_u32 s27, s73, 0
	s_add_u32 s28, s74, s30
	s_addc_u32 s29, s75, 0
	s_add_u32 s94, s94, 0x2000
	s_and_b32 s94, s94, 0x3ffff
	global_load_dwordx4 v[146:149], v184, s[26:27] offset:-4096 nt
	global_load_dwordx4 v[150:153], v184, s[28:29] offset:-4096 nt
	global_load_dwordx4 v[154:157], v184, s[26:27] nt
	global_load_dwordx4 v[158:161], v184, s[28:29] nt
	s_waitcnt vmcnt(0)
	v_cvt_pk_bf16_f32 v244, v146, v147
	v_cvt_pk_bf16_f32 v245, v148, v149
	ds_write_b64 v216, v[244:245]
	v_cvt_pk_bf16_f32 v180, v150, v151
	v_cvt_pk_bf16_f32 v181, v152, v153
	ds_write_b64 v217, v[180:181] offset:8192
	v_cvt_pk_bf16_f32 v244, v154, v155
	v_cvt_pk_bf16_f32 v245, v156, v157
	ds_write_b64 v218, v[244:245]
	v_cvt_pk_bf16_f32 v180, v158, v159
	v_cvt_pk_bf16_f32 v181, v160, v161
	ds_write_b64 v219, v[180:181] offset:8192
	s_add_u32 s30, s95, s94
	s_add_u32 s26, s72, s30
	s_addc_u32 s27, s73, 0
	s_add_u32 s28, s74, s30
	s_addc_u32 s29, s75, 0
	s_add_u32 s94, s94, 0x2000
	s_and_b32 s94, s94, 0x3ffff
	global_load_dwordx4 v[162:165], v184, s[26:27] offset:-4096 nt
	global_load_dwordx4 v[166:169], v184, s[28:29] offset:-4096 nt
	global_load_dwordx4 v[170:173], v184, s[26:27] nt
	global_load_dwordx4 v[174:177], v184, s[28:29] nt
	s_waitcnt vmcnt(0)
	v_cvt_pk_bf16_f32 v244, v162, v163
	v_cvt_pk_bf16_f32 v245, v164, v165
	ds_write_b64 v220, v[244:245]
	v_cvt_pk_bf16_f32 v180, v166, v167
	v_cvt_pk_bf16_f32 v181, v168, v169
	ds_write_b64 v221, v[180:181] offset:8192
	v_cvt_pk_bf16_f32 v244, v170, v171
	v_cvt_pk_bf16_f32 v245, v172, v173
	ds_write_b64 v227, v[244:245]
	v_cvt_pk_bf16_f32 v180, v174, v175
	v_cvt_pk_bf16_f32 v181, v176, v177
	ds_write_b64 v228, v[180:181] offset:8192
	s_branch .LBB0_543

.LBB0_596:
	s_add_i32 s25, s24, 1
	s_cmp_eq_u32 s24, 15
	s_cbranch_scc1 .Lsp_last_b
	s_waitcnt vmcnt(0)
	v_cvt_pk_bf16_f32 v240, v18, v19
	v_cvt_pk_bf16_f32 v241, v20, v21
	ds_write_b64 v190, v[240:241]
	v_cvt_pk_bf16_f32 v180, v22, v23
	v_cvt_pk_bf16_f32 v181, v24, v25
	ds_write_b64 v191, v[180:181] offset:8192
	v_cvt_pk_bf16_f32 v240, v26, v27
	v_cvt_pk_bf16_f32 v241, v28, v29
	ds_write_b64 v192, v[240:241]
	v_cvt_pk_bf16_f32 v180, v34, v35
	v_cvt_pk_bf16_f32 v181, v36, v37
	ds_write_b64 v193, v[180:181] offset:8192
	s_add_u32 s30, s95, s94
	s_add_u32 s26, s72, s30
	s_addc_u32 s27, s73, 0
	s_add_u32 s28, s74, s30
	s_addc_u32 s29, s75, 0
	s_add_u32 s94, s94, 0x2000
	s_and_b32 s94, s94, 0x3ffff
	global_load_dwordx4 v[30:33], v184, s[26:27] offset:-4096 nt
	global_load_dwordx4 v[38:41], v184, s[28:29] offset:-4096 nt
	global_load_dwordx4 v[42:45], v184, s[26:27] nt
	global_load_dwordx4 v[50:53], v184, s[28:29] nt
	s_waitcnt vmcnt(0)
	v_cvt_pk_bf16_f32 v240, v30, v31
	v_cvt_pk_bf16_f32 v241, v32, v33
	ds_write_b64 v194, v[240:241]
	v_cvt_pk_bf16_f32 v180, v38, v39
	v_cvt_pk_bf16_f32 v181, v40, v41
	ds_write_b64 v195, v[180:181] offset:8192
	v_cvt_pk_bf16_f32 v240, v42, v43
	v_cvt_pk_bf16_f32 v241, v44, v45
	ds_write_b64 v197, v[240:241]
	v_cvt_pk_bf16_f32 v180, v50, v51
	v_cvt_pk_bf16_f32 v181, v52, v53
	ds_write_b64 v198, v[180:181] offset:8192
	s_add_u32 s30, s95, s94
	s_add_u32 s26, s72, s30
	s_addc_u32 s27, s73, 0
	s_add_u32 s28, s74, s30
	s_addc_u32 s29, s75, 0
	s_add_u32 s94, s94, 0x2000
	s_and_b32 s94, s94, 0x3ffff
	global_load_dwordx4 v[46:49], v184, s[26:27] offset:-4096 nt
	global_load_dwordx4 v[54:57], v184, s[28:29] offset:-4096 nt
	global_load_dwordx4 v[58:61], v184, s[26:27] nt
	global_load_dwordx4 v[66:69], v184, s[28:29] nt
	s_waitcnt vmcnt(0)
	v_cvt_pk_bf16_f32 v240, v46, v47
	v_cvt_pk_bf16_f32 v241, v48, v49
	ds_write_b64 v199, v[240:241]
	v_cvt_pk_bf16_f32 v180, v54, v55
	v_cvt_pk_bf16_f32 v181, v56, v57
	ds_write_b64 v200, v[180:181] offset:8192
	v_cvt_pk_bf16_f32 v240, v58, v59
	v_cvt_pk_bf16_f32 v241, v60, v61
	ds_write_b64 v201, v[240:241]
	v_cvt_pk_bf16_f32 v180, v66, v67
	v_cvt_pk_bf16_f32 v181, v68, v69
	ds_write_b64 v202, v[180:181] offset:8192
	s_add_u32 s30, s95, s94
	s_add_u32 s26, s72, s30
	s_addc_u32 s27, s73, 0
	s_add_u32 s28, s74, s30
	s_addc_u32 s29, s75, 0
	s_add_u32 s94, s94, 0x2000
	s_and_b32 s94, s94, 0x3ffff
	global_load_dwordx4 v[62:65], v184, s[26:27] offset:-4096 nt
	global_load_dwordx4 v[70:73], v184, s[28:29] offset:-4096 nt
	global_load_dwordx4 v[74:77], v184, s[26:27] nt
	global_load_dwordx4 v[82:85], v184, s[28:29] nt
	s_waitcnt vmcnt(0)
	v_cvt_pk_bf16_f32 v240, v62, v63
	v_cvt_pk_bf16_f32 v241, v64, v65
	ds_write_b64 v203, v[240:241]
	v_cvt_pk_bf16_f32 v180, v70, v71
	v_cvt_pk_bf16_f32 v181, v72, v73
	ds_write_b64 v204, v[180:181] offset:8192
	v_cvt_pk_bf16_f32 v240, v74, v75
	v_cvt_pk_bf16_f32 v241, v76, v77
	ds_write_b64 v205, v[240:241]
	v_cvt_pk_bf16_f32 v180, v82, v83
	v_cvt_pk_bf16_f32 v181, v84, v85
	ds_write_b64 v206, v[180:181] offset:8192
	s_add_u32 s30, s95, s94
	s_add_u32 s26, s72, s30
	s_addc_u32 s27, s73, 0
	s_add_u32 s28, s74, s30
	s_addc_u32 s29, s75, 0
	s_add_u32 s94, s94, 0x2000
	s_and_b32 s94, s94, 0x3ffff
	global_load_dwordx4 v[78:81], v184, s[26:27] offset:-4096 nt
	global_load_dwordx4 v[86:89], v184, s[28:29] offset:-4096 nt
	global_load_dwordx4 v[90:93], v184, s[26:27] nt
	global_load_dwordx4 v[110:113], v184, s[28:29] nt
	s_waitcnt vmcnt(0)
	v_cvt_pk_bf16_f32 v240, v78, v79
	v_cvt_pk_bf16_f32 v241, v80, v81
	ds_write_b64 v190, v[240:241] offset:4096
	v_cvt_pk_bf16_f32 v180, v86, v87
	v_cvt_pk_bf16_f32 v181, v88, v89
	ds_write_b64 v191, v[180:181] offset:12288
	v_cvt_pk_bf16_f32 v240, v90, v91
	v_cvt_pk_bf16_f32 v241, v92, v93
	ds_write_b64 v207, v[240:241]
	v_cvt_pk_bf16_f32 v180, v110, v111
	v_cvt_pk_bf16_f32 v181, v112, v113
	ds_write_b64 v208, v[180:181] offset:8192
	s_add_u32 s30, s95, s94
	s_add_u32 s26, s72, s30
	s_addc_u32 s27, s73, 0
	s_add_u32 s28, s74, s30
	s_addc_u32 s29, s75, 0
	s_add_u32 s94, s94, 0x2000
	s_and_b32 s94, s94, 0x3ffff
	global_load_dwordx4 v[106:109], v184, s[26:27] offset:-4096 nt
	global_load_dwordx4 v[118:121], v184, s[28:29] offset:-4096 nt
	global_load_dwordx4 v[138:141], v184, s[26:27] nt
	global_load_dwordx4 v[142:145], v184, s[28:29] nt
	s_waitcnt vmcnt(0)
	v_cvt_pk_bf16_f32 v240, v106, v107
	v_cvt_pk_bf16_f32 v241, v108, v109
	ds_write_b64 v209, v[240:241]
	v_cvt_pk_bf16_f32 v180, v118, v119
	v_cvt_pk_bf16_f32 v181, v120, v121
	ds_write_b64 v210, v[180:181] offset:8192
	v_cvt_pk_bf16_f32 v240, v138, v139
	v_cvt_pk_bf16_f32 v241, v140, v141
	ds_write_b64 v211, v[240:241]
	v_cvt_pk_bf16_f32 v180, v142, v143
	v_cvt_pk_bf16_f32 v181, v144, v145
	ds_write_b64 v212, v[180:181] offset:8192
	s_add_u32 s30, s95, s94
	s_add_u32 s26, s72, s30
	s_addc_u32 s27, s73, 0
	s_add_u32 s28, s74, s30
	s_addc_u32 s29, s75, 0
	s_add_u32 s94, s94, 0x2000
	s_and_b32 s94, s94, 0x3ffff
	global_load_dwordx4 v[146:149], v184, s[26:27] offset:-4096 nt
	global_load_dwordx4 v[150:153], v184, s[28:29] offset:-4096 nt
	global_load_dwordx4 v[154:157], v184, s[26:27] nt
	global_load_dwordx4 v[158:161], v184, s[28:29] nt
	s_waitcnt vmcnt(0)
	v_cvt_pk_bf16_f32 v240, v146, v147
	v_cvt_pk_bf16_f32 v241, v148, v149
	ds_write_b64 v213, v[240:241]
	v_cvt_pk_bf16_f32 v180, v150, v151
	v_cvt_pk_bf16_f32 v181, v152, v153
	ds_write_b64 v214, v[180:181] offset:8192
	v_cvt_pk_bf16_f32 v240, v154, v155
	v_cvt_pk_bf16_f32 v241, v156, v157
	ds_write_b64 v215, v[240:241]
	v_cvt_pk_bf16_f32 v180, v158, v159
	v_cvt_pk_bf16_f32 v181, v160, v161
	ds_write_b64 v216, v[180:181] offset:8192
	s_add_u32 s30, s95, s94
	s_add_u32 s26, s72, s30
	s_addc_u32 s27, s73, 0
	s_add_u32 s28, s74, s30
	s_addc_u32 s29, s75, 0
	s_add_u32 s94, s94, 0x2000
	s_and_b32 s94, s94, 0x3ffff
	global_load_dwordx4 v[162:165], v184, s[26:27] offset:-4096 nt
	global_load_dwordx4 v[166:169], v184, s[28:29] offset:-4096 nt
	global_load_dwordx4 v[170:173], v184, s[26:27] nt
	global_load_dwordx4 v[174:177], v184, s[28:29] nt
	s_lshr_b32 s30, s25, 2
	s_cmp_lt_u32 s30, 2
	s_cselect_b32 s95, s98, s100
	s_cselect_b32 s97, s99, s101
	s_bitcmp1_b32 s30, 0
	s_cselect_b32 s95, s97, s95
	s_lshl_b32 s95, s95, 18
	s_add_u32 s95, s95, 0x1000
	s_waitcnt vmcnt(0)
	v_cvt_pk_bf16_f32 v240, v162, v163
	v_cvt_pk_bf16_f32 v241, v164, v165
	ds_write_b64 v217, v[240:241]
	v_cvt_pk_bf16_f32 v180, v166, v167
	v_cvt_pk_bf16_f32 v181, v168, v169
	ds_write_b64 v218, v[180:181] offset:8192
	v_cvt_pk_bf16_f32 v240, v170, v171
	v_cvt_pk_bf16_f32 v241, v172, v173
	ds_write_b64 v219, v[240:241]
	v_cvt_pk_bf16_f32 v180, v174, v175
	v_cvt_pk_bf16_f32 v181, v176, v177
	ds_write_b64 v220, v[180:181] offset:8192
	s_add_u32 s30, s95, s94
	s_add_u32 s26, s72, s30
	s_addc_u32 s27, s73, 0
	s_add_u32 s28, s74, s30
	s_addc_u32 s29, s75, 0
	s_add_u32 s94, s94, 0x2000
	s_and_b32 s94, s94, 0x3ffff
	global_load_dwordx4 v[18:21], v184, s[26:27] offset:-4096 nt
	global_load_dwordx4 v[22:25], v184, s[28:29] offset:-4096 nt
	global_load_dwordx4 v[26:29], v184, s[26:27] nt
	global_load_dwordx4 v[34:37], v184, s[28:29] nt
	s_branch .LBB0_600
.Lsp_last_b:
	s_waitcnt vmcnt(0)
	v_cvt_pk_bf16_f32 v240, v18, v19
	v_cvt_pk_bf16_f32 v241, v20, v21
	ds_write_b64 v190, v[240:241]
	v_cvt_pk_bf16_f32 v180, v22, v23
	v_cvt_pk_bf16_f32 v181, v24, v25
	ds_write_b64 v191, v[180:181] offset:8192
	v_cvt_pk_bf16_f32 v240, v26, v27
	v_cvt_pk_bf16_f32 v241, v28, v29
	ds_write_b64 v192, v[240:241]
	v_cvt_pk_bf16_f32 v180, v34, v35
	v_cvt_pk_bf16_f32 v181, v36, v37
	ds_write_b64 v193, v[180:181] offset:8192
	s_add_u32 s30, s95, s94
	s_add_u32 s26, s72, s30
	s_addc_u32 s27, s73, 0
	s_add_u32 s28, s74, s30
	s_addc_u32 s29, s75, 0
	s_add_u32 s94, s94, 0x2000
	s_and_b32 s94, s94, 0x3ffff
	global_load_dwordx4 v[30:33], v184, s[26:27] offset:-4096 nt
	global_load_dwordx4 v[38:41], v184, s[28:29] offset:-4096 nt
	global_load_dwordx4 v[42:45], v184, s[26:27] nt
	global_load_dwordx4 v[50:53], v184, s[28:29] nt
	s_waitcnt vmcnt(0)
	v_cvt_pk_bf16_f32 v240, v30, v31
	v_cvt_pk_bf16_f32 v241, v32, v33
	ds_write_b64 v194, v[240:241]
	v_cvt_pk_bf16_f32 v180, v38, v39
	v_cvt_pk_bf16_f32 v181, v40, v41
	ds_write_b64 v195, v[180:181] offset:8192
	v_cvt_pk_bf16_f32 v240, v42, v43
	v_cvt_pk_bf16_f32 v241, v44, v45
	ds_write_b64 v197, v[240:241]
	v_cvt_pk_bf16_f32 v180, v50, v51
	v_cvt_pk_bf16_f32 v181, v52, v53
	ds_write_b64 v198, v[180:181] offset:8192
	s_add_u32 s30, s95, s94
	s_add_u32 s26, s72, s30
	s_addc_u32 s27, s73, 0
	s_add_u32 s28, s74, s30
	s_addc_u32 s29, s75, 0
	s_add_u32 s94, s94, 0x2000
	s_and_b32 s94, s94, 0x3ffff
	global_load_dwordx4 v[46:49], v184, s[26:27] offset:-4096 nt
	global_load_dwordx4 v[54:57], v184, s[28:29] offset:-4096 nt
	global_load_dwordx4 v[58:61], v184, s[26:27] nt
	global_load_dwordx4 v[66:69], v184, s[28:29] nt
	s_waitcnt vmcnt(0)
	v_cvt_pk_bf16_f32 v240, v46, v47
	v_cvt_pk_bf16_f32 v241, v48, v49
	ds_write_b64 v199, v[240:241]
	v_cvt_pk_bf16_f32 v180, v54, v55
	v_cvt_pk_bf16_f32 v181, v56, v57
	ds_write_b64 v200, v[180:181] offset:8192
	v_cvt_pk_bf16_f32 v240, v58, v59
	v_cvt_pk_bf16_f32 v241, v60, v61
	ds_write_b64 v201, v[240:241]
	v_cvt_pk_bf16_f32 v180, v66, v67
	v_cvt_pk_bf16_f32 v181, v68, v69
	ds_write_b64 v202, v[180:181] offset:8192
	s_add_u32 s30, s95, s94
	s_add_u32 s26, s72, s30
	s_addc_u32 s27, s73, 0
	s_add_u32 s28, s74, s30
	s_addc_u32 s29, s75, 0
	s_add_u32 s94, s94, 0x2000
	s_and_b32 s94, s94, 0x3ffff
	global_load_dwordx4 v[62:65], v184, s[26:27] offset:-4096 nt
	global_load_dwordx4 v[70:73], v184, s[28:29] offset:-4096 nt
	global_load_dwordx4 v[74:77], v184, s[26:27] nt
	global_load_dwordx4 v[82:85], v184, s[28:29] nt
	s_waitcnt vmcnt(0)
	v_cvt_pk_bf16_f32 v240, v62, v63
	v_cvt_pk_bf16_f32 v241, v64, v65
	ds_write_b64 v203, v[240:241]
	v_cvt_pk_bf16_f32 v180, v70, v71
	v_cvt_pk_bf16_f32 v181, v72, v73
	ds_write_b64 v204, v[180:181] offset:8192
	v_cvt_pk_bf16_f32 v240, v74, v75
	v_cvt_pk_bf16_f32 v241, v76, v77
	ds_write_b64 v205, v[240:241]
	v_cvt_pk_bf16_f32 v180, v82, v83
	v_cvt_pk_bf16_f32 v181, v84, v85
	ds_write_b64 v206, v[180:181] offset:8192
	s_add_u32 s30, s95, s94
	s_add_u32 s26, s72, s30
	s_addc_u32 s27, s73, 0
	s_add_u32 s28, s74, s30
	s_addc_u32 s29, s75, 0
	s_add_u32 s94, s94, 0x2000
	s_and_b32 s94, s94, 0x3ffff
	global_load_dwordx4 v[78:81], v184, s[26:27] offset:-4096 nt
	global_load_dwordx4 v[86:89], v184, s[28:29] offset:-4096 nt
	global_load_dwordx4 v[90:93], v184, s[26:27] nt
	global_load_dwordx4 v[110:113], v184, s[28:29] nt
	s_waitcnt vmcnt(0)
	v_cvt_pk_bf16_f32 v240, v78, v79
	v_cvt_pk_bf16_f32 v241, v80, v81
	ds_write_b64 v190, v[240:241] offset:4096
	v_cvt_pk_bf16_f32 v180, v86, v87
	v_cvt_pk_bf16_f32 v181, v88, v89
	ds_write_b64 v191, v[180:181] offset:12288
	v_cvt_pk_bf16_f32 v240, v90, v91
	v_cvt_pk_bf16_f32 v241, v92, v93
	ds_write_b64 v207, v[240:241]
	v_cvt_pk_bf16_f32 v180, v110, v111
	v_cvt_pk_bf16_f32 v181, v112, v113
	ds_write_b64 v208, v[180:181] offset:8192
	s_add_u32 s30, s95, s94
	s_add_u32 s26, s72, s30
	s_addc_u32 s27, s73, 0
	s_add_u32 s28, s74, s30
	s_addc_u32 s29, s75, 0
	s_add_u32 s94, s94, 0x2000
	s_and_b32 s94, s94, 0x3ffff
	global_load_dwordx4 v[106:109], v184, s[26:27] offset:-4096 nt
	global_load_dwordx4 v[118:121], v184, s[28:29] offset:-4096 nt
	global_load_dwordx4 v[138:141], v184, s[26:27] nt
	global_load_dwordx4 v[142:145], v184, s[28:29] nt
	s_waitcnt vmcnt(0)
	v_cvt_pk_bf16_f32 v240, v106, v107
	v_cvt_pk_bf16_f32 v241, v108, v109
	ds_write_b64 v209, v[240:241]
	v_cvt_pk_bf16_f32 v180, v118, v119
	v_cvt_pk_bf16_f32 v181, v120, v121
	ds_write_b64 v210, v[180:181] offset:8192
	v_cvt_pk_bf16_f32 v240, v138, v139
	v_cvt_pk_bf16_f32 v241, v140, v141
	ds_write_b64 v211, v[240:241]
	v_cvt_pk_bf16_f32 v180, v142, v143
	v_cvt_pk_bf16_f32 v181, v144, v145
	ds_write_b64 v212, v[180:181] offset:8192
	s_add_u32 s30, s95, s94
	s_add_u32 s26, s72, s30
	s_addc_u32 s27, s73, 0
	s_add_u32 s28, s74, s30
	s_addc_u32 s29, s75, 0
	s_add_u32 s94, s94, 0x2000
	s_and_b32 s94, s94, 0x3ffff
	global_load_dwordx4 v[146:149], v184, s[26:27] offset:-4096 nt
	global_load_dwordx4 v[150:153], v184, s[28:29] offset:-4096 nt
	global_load_dwordx4 v[154:157], v184, s[26:27] nt
	global_load_dwordx4 v[158:161], v184, s[28:29] nt
	s_waitcnt vmcnt(0)
	v_cvt_pk_bf16_f32 v240, v146, v147
	v_cvt_pk_bf16_f32 v241, v148, v149
	ds_write_b64 v213, v[240:241]
	v_cvt_pk_bf16_f32 v180, v150, v151
	v_cvt_pk_bf16_f32 v181, v152, v153
	ds_write_b64 v214, v[180:181] offset:8192
	v_cvt_pk_bf16_f32 v240, v154, v155
	v_cvt_pk_bf16_f32 v241, v156, v157
	ds_write_b64 v215, v[240:241]
	v_cvt_pk_bf16_f32 v180, v158, v159
	v_cvt_pk_bf16_f32 v181, v160, v161
	ds_write_b64 v216, v[180:181] offset:8192
	s_add_u32 s30, s95, s94
	s_add_u32 s26, s72, s30
	s_addc_u32 s27, s73, 0
	s_add_u32 s28, s74, s30
	s_addc_u32 s29, s75, 0
	s_add_u32 s94, s94, 0x2000
	s_and_b32 s94, s94, 0x3ffff
	global_load_dwordx4 v[162:165], v184, s[26:27] offset:-4096 nt
	global_load_dwordx4 v[166:169], v184, s[28:29] offset:-4096 nt
	global_load_dwordx4 v[170:173], v184, s[26:27] nt
	global_load_dwordx4 v[174:177], v184, s[28:29] nt
	s_waitcnt vmcnt(0)
	v_cvt_pk_bf16_f32 v240, v162, v163
	v_cvt_pk_bf16_f32 v241, v164, v165
	ds_write_b64 v217, v[240:241]
	v_cvt_pk_bf16_f32 v180, v166, v167
	v_cvt_pk_bf16_f32 v181, v168, v169
	ds_write_b64 v218, v[180:181] offset:8192
	v_cvt_pk_bf16_f32 v240, v170, v171
	v_cvt_pk_bf16_f32 v241, v172, v173
	ds_write_b64 v219, v[240:241]
	v_cvt_pk_bf16_f32 v180, v174, v175
	v_cvt_pk_bf16_f32 v181, v176, v177
	ds_write_b64 v220, v[180:181] offset:8192
	s_branch .LBB0_600
